# m28 + index selection: level-2 histogram counts in the high 16 bits of the table words (increment 0x10000, scan compares against k<<16), so the table is not cleared between level 1 and level 2 (one of
# speedup vs baseline: 1.0029x; 1.0029x over previous
.LBB0_1397:
	s_mov_b32 s68, s69
	s_mov_b32 s70, s69
	s_mov_b32 s71, s69
	v_mov_b64_e32 v[6:7], s[68:69]
	v_add_u32_e32 v3, s66, v39
	v_mov_b64_e32 v[8:9], s[70:71]
	v_lshlrev_b32_e32 v4, 4, v167
	v_readlane_b32 s0, v251, 31
	v_add_u32_e32 v6, s0, v4
	s_waitcnt lgkmcnt(0)
	s_barrier
	ds_read_b32 v7, v6 offset:8
	s_waitcnt lgkmcnt(0)
	v_cmp_ne_u32_e32 vcc, 0, v7
	s_and_saveexec_b64 s[42:43], vcc
	s_cbranch_execz .LBB0_1717
	ds_read_b32 v6, v6
	v_mov_b32_e32 v9, 0x10000
	s_and_b64 vcc, exec, s[78:79]
	s_cbranch_vccz .LBB0_1408
	v_lshrrev_b32_e32 v7, 21, v171
	s_waitcnt lgkmcnt(0)
	v_cmp_eq_u32_e32 vcc, v7, v6
	s_and_saveexec_b64 s[0:1], vcc
	v_lshrrev_b32_e32 v7, 13, v171
	v_bfe_u32 v8, v171, 10, 11
	v_bitop3_b32 v7, v7, v8, 28 bitop3:0x6c
	v_lshl_add_u32 v7, v7, 2, v40
	ds_add_u32 v7, v9
	s_or_b64 exec, exec, s[0:1]
	v_lshrrev_b32_e32 v7, 21, v170
	v_cmp_eq_u32_e32 vcc, v7, v6
	s_and_saveexec_b64 s[0:1], vcc
	v_lshrrev_b32_e32 v7, 13, v170
	v_bfe_u32 v8, v170, 10, 11
	v_bitop3_b32 v7, v7, v8, 28 bitop3:0x6c
	v_lshl_add_u32 v7, v7, 2, v40
	ds_add_u32 v7, v9
	s_or_b64 exec, exec, s[0:1]
	v_lshrrev_b32_e32 v7, 21, v169
	v_cmp_eq_u32_e32 vcc, v7, v6
	s_and_saveexec_b64 s[0:1], vcc
	v_lshrrev_b32_e32 v7, 13, v169
	v_bfe_u32 v8, v169, 10, 11
	v_bitop3_b32 v7, v7, v8, 28 bitop3:0x6c
	v_lshl_add_u32 v7, v7, 2, v40
	ds_add_u32 v7, v9
	s_or_b64 exec, exec, s[0:1]
	v_lshrrev_b32_e32 v7, 21, v168
	v_cmp_eq_u32_e32 vcc, v7, v6
	s_and_saveexec_b64 s[0:1], vcc
	v_lshrrev_b32_e32 v7, 13, v168
	v_bfe_u32 v8, v168, 10, 11
	v_bitop3_b32 v7, v7, v8, 28 bitop3:0x6c
	v_lshl_add_u32 v7, v7, 2, v40
	ds_add_u32 v7, v9
	s_or_b64 exec, exec, s[0:1]
.LBB0_1408:
	s_cmp_lt_i32 s77, 8
	s_cbranch_scc1 .LBB0_1559
	v_lshrrev_b32_e32 v7, 21, v166
	s_waitcnt lgkmcnt(0)
	v_cmp_eq_u32_e32 vcc, v7, v6
	s_and_saveexec_b64 s[0:1], vcc
	v_lshrrev_b32_e32 v7, 13, v166
	v_bfe_u32 v8, v166, 10, 11
	v_bitop3_b32 v7, v7, v8, 28 bitop3:0x6c
	v_lshl_add_u32 v7, v7, 2, v40
	ds_add_u32 v7, v9
	s_or_b64 exec, exec, s[0:1]
	v_lshrrev_b32_e32 v7, 21, v165
	v_cmp_eq_u32_e32 vcc, v7, v6
	s_and_saveexec_b64 s[0:1], vcc
	v_lshrrev_b32_e32 v7, 13, v165
	v_bfe_u32 v8, v165, 10, 11
	v_bitop3_b32 v7, v7, v8, 28 bitop3:0x6c
	v_lshl_add_u32 v7, v7, 2, v40
	ds_add_u32 v7, v9
	s_or_b64 exec, exec, s[0:1]
	v_lshrrev_b32_e32 v7, 21, v164
	v_cmp_eq_u32_e32 vcc, v7, v6
	s_and_saveexec_b64 s[0:1], vcc
	v_lshrrev_b32_e32 v7, 13, v164
	v_bfe_u32 v8, v164, 10, 11
	v_bitop3_b32 v7, v7, v8, 28 bitop3:0x6c
	v_lshl_add_u32 v7, v7, 2, v40
	ds_add_u32 v7, v9
	s_or_b64 exec, exec, s[0:1]
	v_lshrrev_b32_e32 v7, 21, v163
	v_cmp_eq_u32_e32 vcc, v7, v6
	s_and_saveexec_b64 s[0:1], vcc
	v_lshrrev_b32_e32 v7, 13, v163
	v_bfe_u32 v8, v163, 10, 11
	v_bitop3_b32 v7, v7, v8, 28 bitop3:0x6c
	v_lshl_add_u32 v7, v7, 2, v40
	ds_add_u32 v7, v9
	s_or_b64 exec, exec, s[0:1]
	s_cmp_lt_i32 s77, 16
	s_cbranch_scc0 .LBB0_1560

.LBB0_1419:
	v_lshrrev_b32_e32 v7, 21, v158
	s_waitcnt lgkmcnt(0)
	v_cmp_eq_u32_e32 vcc, v7, v6
	s_and_saveexec_b64 s[0:1], vcc
	v_lshrrev_b32_e32 v7, 13, v158
	v_bfe_u32 v8, v158, 10, 11
	v_bitop3_b32 v7, v7, v8, 28 bitop3:0x6c
	v_lshl_add_u32 v7, v7, 2, v40
	ds_add_u32 v7, v9
	s_or_b64 exec, exec, s[0:1]
	v_lshrrev_b32_e32 v7, 21, v157
	v_cmp_eq_u32_e32 vcc, v7, v6
	s_and_saveexec_b64 s[0:1], vcc
	v_lshrrev_b32_e32 v7, 13, v157
	v_bfe_u32 v8, v157, 10, 11
	v_bitop3_b32 v7, v7, v8, 28 bitop3:0x6c
	v_lshl_add_u32 v7, v7, 2, v40
	ds_add_u32 v7, v9
	s_or_b64 exec, exec, s[0:1]
	v_lshrrev_b32_e32 v7, 21, v156
	v_cmp_eq_u32_e32 vcc, v7, v6
	s_and_saveexec_b64 s[0:1], vcc
	v_lshrrev_b32_e32 v7, 13, v156
	v_bfe_u32 v8, v156, 10, 11
	v_bitop3_b32 v7, v7, v8, 28 bitop3:0x6c
	v_lshl_add_u32 v7, v7, 2, v40
	ds_add_u32 v7, v9
	s_or_b64 exec, exec, s[0:1]
	v_lshrrev_b32_e32 v7, 21, v155
	v_cmp_eq_u32_e32 vcc, v7, v6
	s_and_saveexec_b64 s[0:1], vcc
	v_lshrrev_b32_e32 v7, 13, v155
	v_bfe_u32 v8, v155, 10, 11
	v_bitop3_b32 v7, v7, v8, 28 bitop3:0x6c
	v_lshl_add_u32 v7, v7, 2, v40
	ds_add_u32 v7, v9
	s_or_b64 exec, exec, s[0:1]
	s_cmp_lt_i32 s77, 32
	s_cbranch_scc0 .LBB0_1570

.LBB0_1429:
	v_lshrrev_b32_e32 v7, 21, v150
	s_waitcnt lgkmcnt(0)
	v_cmp_eq_u32_e32 vcc, v7, v6
	s_and_saveexec_b64 s[0:1], vcc
	v_lshrrev_b32_e32 v7, 13, v150
	v_bfe_u32 v8, v150, 10, 11
	v_bitop3_b32 v7, v7, v8, 28 bitop3:0x6c
	v_lshl_add_u32 v7, v7, 2, v40
	ds_add_u32 v7, v9
	s_or_b64 exec, exec, s[0:1]
	v_lshrrev_b32_e32 v7, 21, v149
	v_cmp_eq_u32_e32 vcc, v7, v6
	s_and_saveexec_b64 s[0:1], vcc
	v_lshrrev_b32_e32 v7, 13, v149
	v_bfe_u32 v8, v149, 10, 11
	v_bitop3_b32 v7, v7, v8, 28 bitop3:0x6c
	v_lshl_add_u32 v7, v7, 2, v40
	ds_add_u32 v7, v9
	s_or_b64 exec, exec, s[0:1]
	v_lshrrev_b32_e32 v7, 21, v148
	v_cmp_eq_u32_e32 vcc, v7, v6
	s_and_saveexec_b64 s[0:1], vcc
	v_lshrrev_b32_e32 v7, 13, v148
	v_bfe_u32 v8, v148, 10, 11
	v_bitop3_b32 v7, v7, v8, 28 bitop3:0x6c
	v_lshl_add_u32 v7, v7, 2, v40
	ds_add_u32 v7, v9
	s_or_b64 exec, exec, s[0:1]
	v_lshrrev_b32_e32 v7, 21, v147
	v_cmp_eq_u32_e32 vcc, v7, v6
	s_and_saveexec_b64 s[0:1], vcc
	v_lshrrev_b32_e32 v7, 13, v147
	v_bfe_u32 v8, v147, 10, 11
	v_bitop3_b32 v7, v7, v8, 28 bitop3:0x6c
	v_lshl_add_u32 v7, v7, 2, v40
	ds_add_u32 v7, v9
	s_or_b64 exec, exec, s[0:1]
	s_cmp_lt_i32 s77, 48
	s_cbranch_scc0 .LBB0_1580

.LBB0_1439:
	v_lshrrev_b32_e32 v7, 21, v142
	s_waitcnt lgkmcnt(0)
	v_cmp_eq_u32_e32 vcc, v7, v6
	s_and_saveexec_b64 s[0:1], vcc
	v_lshrrev_b32_e32 v7, 13, v142
	v_bfe_u32 v8, v142, 10, 11
	v_bitop3_b32 v7, v7, v8, 28 bitop3:0x6c
	v_lshl_add_u32 v7, v7, 2, v40
	ds_add_u32 v7, v9
	s_or_b64 exec, exec, s[0:1]
	v_lshrrev_b32_e32 v7, 21, v141
	v_cmp_eq_u32_e32 vcc, v7, v6
	s_and_saveexec_b64 s[0:1], vcc
	v_lshrrev_b32_e32 v7, 13, v141
	v_bfe_u32 v8, v141, 10, 11
	v_bitop3_b32 v7, v7, v8, 28 bitop3:0x6c
	v_lshl_add_u32 v7, v7, 2, v40
	ds_add_u32 v7, v9
	s_or_b64 exec, exec, s[0:1]
	v_lshrrev_b32_e32 v7, 21, v140
	v_cmp_eq_u32_e32 vcc, v7, v6
	s_and_saveexec_b64 s[0:1], vcc
	v_lshrrev_b32_e32 v7, 13, v140
	v_bfe_u32 v8, v140, 10, 11
	v_bitop3_b32 v7, v7, v8, 28 bitop3:0x6c
	v_lshl_add_u32 v7, v7, 2, v40
	ds_add_u32 v7, v9
	s_or_b64 exec, exec, s[0:1]
	v_lshrrev_b32_e32 v7, 21, v139
	v_cmp_eq_u32_e32 vcc, v7, v6
	s_and_saveexec_b64 s[0:1], vcc
	v_lshrrev_b32_e32 v7, 13, v139
	v_bfe_u32 v8, v139, 10, 11
	v_bitop3_b32 v7, v7, v8, 28 bitop3:0x6c
	v_lshl_add_u32 v7, v7, 2, v40
	ds_add_u32 v7, v9
	s_or_b64 exec, exec, s[0:1]
	s_cmp_lt_i32 s77, 64
	s_cbranch_scc0 .LBB0_1590

.LBB0_1449:
	v_lshrrev_b32_e32 v7, 21, v134
	s_waitcnt lgkmcnt(0)
	v_cmp_eq_u32_e32 vcc, v7, v6
	s_and_saveexec_b64 s[0:1], vcc
	v_lshrrev_b32_e32 v7, 13, v134
	v_bfe_u32 v8, v134, 10, 11
	v_bitop3_b32 v7, v7, v8, 28 bitop3:0x6c
	v_lshl_add_u32 v7, v7, 2, v40
	ds_add_u32 v7, v9
	s_or_b64 exec, exec, s[0:1]
	v_lshrrev_b32_e32 v7, 21, v133
	v_cmp_eq_u32_e32 vcc, v7, v6
	s_and_saveexec_b64 s[0:1], vcc
	v_lshrrev_b32_e32 v7, 13, v133
	v_bfe_u32 v8, v133, 10, 11
	v_bitop3_b32 v7, v7, v8, 28 bitop3:0x6c
	v_lshl_add_u32 v7, v7, 2, v40
	ds_add_u32 v7, v9
	s_or_b64 exec, exec, s[0:1]
	v_lshrrev_b32_e32 v7, 21, v132
	v_cmp_eq_u32_e32 vcc, v7, v6
	s_and_saveexec_b64 s[0:1], vcc
	v_lshrrev_b32_e32 v7, 13, v132
	v_bfe_u32 v8, v132, 10, 11
	v_bitop3_b32 v7, v7, v8, 28 bitop3:0x6c
	v_lshl_add_u32 v7, v7, 2, v40
	ds_add_u32 v7, v9
	s_or_b64 exec, exec, s[0:1]
	v_lshrrev_b32_e32 v7, 21, v131
	v_cmp_eq_u32_e32 vcc, v7, v6
	s_and_saveexec_b64 s[0:1], vcc
	v_lshrrev_b32_e32 v7, 13, v131
	v_bfe_u32 v8, v131, 10, 11
	v_bitop3_b32 v7, v7, v8, 28 bitop3:0x6c
	v_lshl_add_u32 v7, v7, 2, v40
	ds_add_u32 v7, v9
	s_or_b64 exec, exec, s[0:1]
	s_cmpk_lt_i32 s77, 0x50
	s_cbranch_scc0 .LBB0_1600

.LBB0_1459:
	v_lshrrev_b32_e32 v7, 21, v126
	s_waitcnt lgkmcnt(0)
	v_cmp_eq_u32_e32 vcc, v7, v6
	s_and_saveexec_b64 s[0:1], vcc
	v_lshrrev_b32_e32 v7, 13, v126
	v_bfe_u32 v8, v126, 10, 11
	v_bitop3_b32 v7, v7, v8, 28 bitop3:0x6c
	v_lshl_add_u32 v7, v7, 2, v40
	ds_add_u32 v7, v9
	s_or_b64 exec, exec, s[0:1]
	v_lshrrev_b32_e32 v7, 21, v125
	v_cmp_eq_u32_e32 vcc, v7, v6
	s_and_saveexec_b64 s[0:1], vcc
	v_lshrrev_b32_e32 v7, 13, v125
	v_bfe_u32 v8, v125, 10, 11
	v_bitop3_b32 v7, v7, v8, 28 bitop3:0x6c
	v_lshl_add_u32 v7, v7, 2, v40
	ds_add_u32 v7, v9
	s_or_b64 exec, exec, s[0:1]
	v_lshrrev_b32_e32 v7, 21, v124
	v_cmp_eq_u32_e32 vcc, v7, v6
	s_and_saveexec_b64 s[0:1], vcc
	v_lshrrev_b32_e32 v7, 13, v124
	v_bfe_u32 v8, v124, 10, 11
	v_bitop3_b32 v7, v7, v8, 28 bitop3:0x6c
	v_lshl_add_u32 v7, v7, 2, v40
	ds_add_u32 v7, v9
	s_or_b64 exec, exec, s[0:1]
	v_lshrrev_b32_e32 v7, 21, v123
	v_cmp_eq_u32_e32 vcc, v7, v6
	s_and_saveexec_b64 s[0:1], vcc
	v_lshrrev_b32_e32 v7, 13, v123
	v_bfe_u32 v8, v123, 10, 11
	v_bitop3_b32 v7, v7, v8, 28 bitop3:0x6c
	v_lshl_add_u32 v7, v7, 2, v40
	ds_add_u32 v7, v9
	s_or_b64 exec, exec, s[0:1]
	s_cmpk_lt_i32 s77, 0x60
	s_cbranch_scc0 .LBB0_1610

.LBB0_1469:
	v_lshrrev_b32_e32 v7, 21, v118
	s_waitcnt lgkmcnt(0)
	v_cmp_eq_u32_e32 vcc, v7, v6
	s_and_saveexec_b64 s[0:1], vcc
	v_lshrrev_b32_e32 v7, 13, v118
	v_bfe_u32 v8, v118, 10, 11
	v_bitop3_b32 v7, v7, v8, 28 bitop3:0x6c
	v_lshl_add_u32 v7, v7, 2, v40
	ds_add_u32 v7, v9
	s_or_b64 exec, exec, s[0:1]
	v_lshrrev_b32_e32 v7, 21, v117
	v_cmp_eq_u32_e32 vcc, v7, v6
	s_and_saveexec_b64 s[0:1], vcc
	v_lshrrev_b32_e32 v7, 13, v117
	v_bfe_u32 v8, v117, 10, 11
	v_bitop3_b32 v7, v7, v8, 28 bitop3:0x6c
	v_lshl_add_u32 v7, v7, 2, v40
	ds_add_u32 v7, v9
	s_or_b64 exec, exec, s[0:1]
	v_lshrrev_b32_e32 v7, 21, v115
	v_cmp_eq_u32_e32 vcc, v7, v6
	s_and_saveexec_b64 s[0:1], vcc
	v_lshrrev_b32_e32 v7, 13, v115
	v_bfe_u32 v8, v115, 10, 11
	v_bitop3_b32 v7, v7, v8, 28 bitop3:0x6c
	v_lshl_add_u32 v7, v7, 2, v40
	ds_add_u32 v7, v9
	s_or_b64 exec, exec, s[0:1]
	v_lshrrev_b32_e32 v7, 21, v114
	v_cmp_eq_u32_e32 vcc, v7, v6
	s_and_saveexec_b64 s[0:1], vcc
	v_lshrrev_b32_e32 v7, 13, v114
	v_bfe_u32 v8, v114, 10, 11
	v_bitop3_b32 v7, v7, v8, 28 bitop3:0x6c
	v_lshl_add_u32 v7, v7, 2, v40
	ds_add_u32 v7, v9
	s_or_b64 exec, exec, s[0:1]
	s_cmpk_lt_i32 s77, 0x70
	s_cbranch_scc0 .LBB0_1620

.LBB0_1479:
	v_lshrrev_b32_e32 v7, 21, v109
	s_waitcnt lgkmcnt(0)
	v_cmp_eq_u32_e32 vcc, v7, v6
	s_and_saveexec_b64 s[0:1], vcc
	v_lshrrev_b32_e32 v7, 13, v109
	v_bfe_u32 v8, v109, 10, 11
	v_bitop3_b32 v7, v7, v8, 28 bitop3:0x6c
	v_lshl_add_u32 v7, v7, 2, v40
	ds_add_u32 v7, v9
	s_or_b64 exec, exec, s[0:1]
	v_lshrrev_b32_e32 v7, 21, v108
	v_cmp_eq_u32_e32 vcc, v7, v6
	s_and_saveexec_b64 s[0:1], vcc
	v_lshrrev_b32_e32 v7, 13, v108
	v_bfe_u32 v8, v108, 10, 11
	v_bitop3_b32 v7, v7, v8, 28 bitop3:0x6c
	v_lshl_add_u32 v7, v7, 2, v40
	ds_add_u32 v7, v9
	s_or_b64 exec, exec, s[0:1]
	v_lshrrev_b32_e32 v7, 21, v107
	v_cmp_eq_u32_e32 vcc, v7, v6
	s_and_saveexec_b64 s[0:1], vcc
	v_lshrrev_b32_e32 v7, 13, v107
	v_bfe_u32 v8, v107, 10, 11
	v_bitop3_b32 v7, v7, v8, 28 bitop3:0x6c
	v_lshl_add_u32 v7, v7, 2, v40
	ds_add_u32 v7, v9
	s_or_b64 exec, exec, s[0:1]
	v_lshrrev_b32_e32 v7, 21, v105
	v_cmp_eq_u32_e32 vcc, v7, v6
	s_and_saveexec_b64 s[0:1], vcc
	v_lshrrev_b32_e32 v7, 13, v105
	v_bfe_u32 v8, v105, 10, 11
	v_bitop3_b32 v7, v7, v8, 28 bitop3:0x6c
	v_lshl_add_u32 v7, v7, 2, v40
	ds_add_u32 v7, v9
	s_or_b64 exec, exec, s[0:1]
	s_cmpk_lt_i32 s77, 0x80
	s_cbranch_scc0 .LBB0_1630

.LBB0_1489:
	v_lshrrev_b32_e32 v7, 21, v101
	s_waitcnt lgkmcnt(0)
	v_cmp_eq_u32_e32 vcc, v7, v6
	s_and_saveexec_b64 s[0:1], vcc
	v_lshrrev_b32_e32 v7, 13, v101
	v_bfe_u32 v8, v101, 10, 11
	v_bitop3_b32 v7, v7, v8, 28 bitop3:0x6c
	v_lshl_add_u32 v7, v7, 2, v40
	ds_add_u32 v7, v9
	s_or_b64 exec, exec, s[0:1]
	v_lshrrev_b32_e32 v7, 21, v100
	v_cmp_eq_u32_e32 vcc, v7, v6
	s_and_saveexec_b64 s[0:1], vcc
	v_lshrrev_b32_e32 v7, 13, v100
	v_bfe_u32 v8, v100, 10, 11
	v_bitop3_b32 v7, v7, v8, 28 bitop3:0x6c
	v_lshl_add_u32 v7, v7, 2, v40
	ds_add_u32 v7, v9
	s_or_b64 exec, exec, s[0:1]
	v_lshrrev_b32_e32 v7, 21, v99
	v_cmp_eq_u32_e32 vcc, v7, v6
	s_and_saveexec_b64 s[0:1], vcc
	v_lshrrev_b32_e32 v7, 13, v99
	v_bfe_u32 v8, v99, 10, 11
	v_bitop3_b32 v7, v7, v8, 28 bitop3:0x6c
	v_lshl_add_u32 v7, v7, 2, v40
	ds_add_u32 v7, v9
	s_or_b64 exec, exec, s[0:1]
	v_lshrrev_b32_e32 v7, 21, v98
	v_cmp_eq_u32_e32 vcc, v7, v6
	s_and_saveexec_b64 s[0:1], vcc
	v_lshrrev_b32_e32 v7, 13, v98
	v_bfe_u32 v8, v98, 10, 11
	v_bitop3_b32 v7, v7, v8, 28 bitop3:0x6c
	v_lshl_add_u32 v7, v7, 2, v40
	ds_add_u32 v7, v9
	s_or_b64 exec, exec, s[0:1]
	s_cmpk_lt_i32 s77, 0x90
	s_cbranch_scc0 .LBB0_1640

.LBB0_1499:
	v_lshrrev_b32_e32 v7, 21, v93
	s_waitcnt lgkmcnt(0)
	v_cmp_eq_u32_e32 vcc, v7, v6
	s_and_saveexec_b64 s[0:1], vcc
	v_lshrrev_b32_e32 v7, 13, v93
	v_bfe_u32 v8, v93, 10, 11
	v_bitop3_b32 v7, v7, v8, 28 bitop3:0x6c
	v_lshl_add_u32 v7, v7, 2, v40
	ds_add_u32 v7, v9
	s_or_b64 exec, exec, s[0:1]
	v_lshrrev_b32_e32 v7, 21, v92
	v_cmp_eq_u32_e32 vcc, v7, v6
	s_and_saveexec_b64 s[0:1], vcc
	v_lshrrev_b32_e32 v7, 13, v92
	v_bfe_u32 v8, v92, 10, 11
	v_bitop3_b32 v7, v7, v8, 28 bitop3:0x6c
	v_lshl_add_u32 v7, v7, 2, v40
	ds_add_u32 v7, v9
	s_or_b64 exec, exec, s[0:1]
	v_lshrrev_b32_e32 v7, 21, v91
	v_cmp_eq_u32_e32 vcc, v7, v6
	s_and_saveexec_b64 s[0:1], vcc
	v_lshrrev_b32_e32 v7, 13, v91
	v_bfe_u32 v8, v91, 10, 11
	v_bitop3_b32 v7, v7, v8, 28 bitop3:0x6c
	v_lshl_add_u32 v7, v7, 2, v40
	ds_add_u32 v7, v9
	s_or_b64 exec, exec, s[0:1]
	v_lshrrev_b32_e32 v7, 21, v90
	v_cmp_eq_u32_e32 vcc, v7, v6
	s_and_saveexec_b64 s[0:1], vcc
	v_lshrrev_b32_e32 v7, 13, v90
	v_bfe_u32 v8, v90, 10, 11
	v_bitop3_b32 v7, v7, v8, 28 bitop3:0x6c
	v_lshl_add_u32 v7, v7, 2, v40
	ds_add_u32 v7, v9
	s_or_b64 exec, exec, s[0:1]
	s_cmpk_lt_i32 s77, 0xa0
	s_cbranch_scc0 .LBB0_1650

.LBB0_1509:
	v_lshrrev_b32_e32 v7, 21, v85
	s_waitcnt lgkmcnt(0)
	v_cmp_eq_u32_e32 vcc, v7, v6
	s_and_saveexec_b64 s[0:1], vcc
	v_lshrrev_b32_e32 v7, 13, v85
	v_bfe_u32 v8, v85, 10, 11
	v_bitop3_b32 v7, v7, v8, 28 bitop3:0x6c
	v_lshl_add_u32 v7, v7, 2, v40
	ds_add_u32 v7, v9
	s_or_b64 exec, exec, s[0:1]
	v_lshrrev_b32_e32 v7, 21, v84
	v_cmp_eq_u32_e32 vcc, v7, v6
	s_and_saveexec_b64 s[0:1], vcc
	v_lshrrev_b32_e32 v7, 13, v84
	v_bfe_u32 v8, v84, 10, 11
	v_bitop3_b32 v7, v7, v8, 28 bitop3:0x6c
	v_lshl_add_u32 v7, v7, 2, v40
	ds_add_u32 v7, v9
	s_or_b64 exec, exec, s[0:1]
	v_lshrrev_b32_e32 v7, 21, v83
	v_cmp_eq_u32_e32 vcc, v7, v6
	s_and_saveexec_b64 s[0:1], vcc
	v_lshrrev_b32_e32 v7, 13, v83
	v_bfe_u32 v8, v83, 10, 11
	v_bitop3_b32 v7, v7, v8, 28 bitop3:0x6c
	v_lshl_add_u32 v7, v7, 2, v40
	ds_add_u32 v7, v9
	s_or_b64 exec, exec, s[0:1]
	v_lshrrev_b32_e32 v7, 21, v82
	v_cmp_eq_u32_e32 vcc, v7, v6
	s_and_saveexec_b64 s[0:1], vcc
	v_lshrrev_b32_e32 v7, 13, v82
	v_bfe_u32 v8, v82, 10, 11
	v_bitop3_b32 v7, v7, v8, 28 bitop3:0x6c
	v_lshl_add_u32 v7, v7, 2, v40
	ds_add_u32 v7, v9
	s_or_b64 exec, exec, s[0:1]
	s_cmpk_lt_i32 s77, 0xb0
	s_cbranch_scc0 .LBB0_1660

.LBB0_1519:
	v_lshrrev_b32_e32 v7, 21, v77
	s_waitcnt lgkmcnt(0)
	v_cmp_eq_u32_e32 vcc, v7, v6
	s_and_saveexec_b64 s[0:1], vcc
	v_lshrrev_b32_e32 v7, 13, v77
	v_bfe_u32 v8, v77, 10, 11
	v_bitop3_b32 v7, v7, v8, 28 bitop3:0x6c
	v_lshl_add_u32 v7, v7, 2, v40
	ds_add_u32 v7, v9
	s_or_b64 exec, exec, s[0:1]
	v_lshrrev_b32_e32 v7, 21, v76
	v_cmp_eq_u32_e32 vcc, v7, v6
	s_and_saveexec_b64 s[0:1], vcc
	v_lshrrev_b32_e32 v7, 13, v76
	v_bfe_u32 v8, v76, 10, 11
	v_bitop3_b32 v7, v7, v8, 28 bitop3:0x6c
	v_lshl_add_u32 v7, v7, 2, v40
	ds_add_u32 v7, v9
	s_or_b64 exec, exec, s[0:1]
	v_lshrrev_b32_e32 v7, 21, v75
	v_cmp_eq_u32_e32 vcc, v7, v6
	s_and_saveexec_b64 s[0:1], vcc
	v_lshrrev_b32_e32 v7, 13, v75
	v_bfe_u32 v8, v75, 10, 11
	v_bitop3_b32 v7, v7, v8, 28 bitop3:0x6c
	v_lshl_add_u32 v7, v7, 2, v40
	ds_add_u32 v7, v9
	s_or_b64 exec, exec, s[0:1]
	v_lshrrev_b32_e32 v7, 21, v74
	v_cmp_eq_u32_e32 vcc, v7, v6
	s_and_saveexec_b64 s[0:1], vcc
	v_lshrrev_b32_e32 v7, 13, v74
	v_bfe_u32 v8, v74, 10, 11
	v_bitop3_b32 v7, v7, v8, 28 bitop3:0x6c
	v_lshl_add_u32 v7, v7, 2, v40
	ds_add_u32 v7, v9
	s_or_b64 exec, exec, s[0:1]
	s_cmpk_lt_i32 s77, 0xc0
	s_cbranch_scc0 .LBB0_1670

.LBB0_1529:
	v_lshrrev_b32_e32 v7, 21, v69
	s_waitcnt lgkmcnt(0)
	v_cmp_eq_u32_e32 vcc, v7, v6
	s_and_saveexec_b64 s[0:1], vcc
	v_lshrrev_b32_e32 v7, 13, v69
	v_bfe_u32 v8, v69, 10, 11
	v_bitop3_b32 v7, v7, v8, 28 bitop3:0x6c
	v_lshl_add_u32 v7, v7, 2, v40
	ds_add_u32 v7, v9
	s_or_b64 exec, exec, s[0:1]
	v_lshrrev_b32_e32 v7, 21, v68
	v_cmp_eq_u32_e32 vcc, v7, v6
	s_and_saveexec_b64 s[0:1], vcc
	v_lshrrev_b32_e32 v7, 13, v68
	v_bfe_u32 v8, v68, 10, 11
	v_bitop3_b32 v7, v7, v8, 28 bitop3:0x6c
	v_lshl_add_u32 v7, v7, 2, v40
	ds_add_u32 v7, v9
	s_or_b64 exec, exec, s[0:1]
	v_lshrrev_b32_e32 v7, 21, v67
	v_cmp_eq_u32_e32 vcc, v7, v6
	s_and_saveexec_b64 s[0:1], vcc
	v_lshrrev_b32_e32 v7, 13, v67
	v_bfe_u32 v8, v67, 10, 11
	v_bitop3_b32 v7, v7, v8, 28 bitop3:0x6c
	v_lshl_add_u32 v7, v7, 2, v40
	ds_add_u32 v7, v9
	s_or_b64 exec, exec, s[0:1]
	v_lshrrev_b32_e32 v7, 21, v66
	v_cmp_eq_u32_e32 vcc, v7, v6
	s_and_saveexec_b64 s[0:1], vcc
	v_lshrrev_b32_e32 v7, 13, v66
	v_bfe_u32 v8, v66, 10, 11
	v_bitop3_b32 v7, v7, v8, 28 bitop3:0x6c
	v_lshl_add_u32 v7, v7, 2, v40
	ds_add_u32 v7, v9
	s_or_b64 exec, exec, s[0:1]
	s_cmpk_lt_i32 s77, 0xd0
	s_cbranch_scc0 .LBB0_1680

.LBB0_1539:
	v_lshrrev_b32_e32 v7, 21, v61
	s_waitcnt lgkmcnt(0)
	v_cmp_eq_u32_e32 vcc, v7, v6
	s_and_saveexec_b64 s[0:1], vcc
	v_lshrrev_b32_e32 v7, 13, v61
	v_bfe_u32 v8, v61, 10, 11
	v_bitop3_b32 v7, v7, v8, 28 bitop3:0x6c
	v_lshl_add_u32 v7, v7, 2, v40
	ds_add_u32 v7, v9
	s_or_b64 exec, exec, s[0:1]
	v_lshrrev_b32_e32 v7, 21, v60
	v_cmp_eq_u32_e32 vcc, v7, v6
	s_and_saveexec_b64 s[0:1], vcc
	v_lshrrev_b32_e32 v7, 13, v60
	v_bfe_u32 v8, v60, 10, 11
	v_bitop3_b32 v7, v7, v8, 28 bitop3:0x6c
	v_lshl_add_u32 v7, v7, 2, v40
	ds_add_u32 v7, v9
	s_or_b64 exec, exec, s[0:1]
	v_lshrrev_b32_e32 v7, 21, v59
	v_cmp_eq_u32_e32 vcc, v7, v6
	s_and_saveexec_b64 s[0:1], vcc
	v_lshrrev_b32_e32 v7, 13, v59
	v_bfe_u32 v8, v59, 10, 11
	v_bitop3_b32 v7, v7, v8, 28 bitop3:0x6c
	v_lshl_add_u32 v7, v7, 2, v40
	ds_add_u32 v7, v9
	s_or_b64 exec, exec, s[0:1]
	v_lshrrev_b32_e32 v7, 21, v58
	v_cmp_eq_u32_e32 vcc, v7, v6
	s_and_saveexec_b64 s[0:1], vcc
	v_lshrrev_b32_e32 v7, 13, v58
	v_bfe_u32 v8, v58, 10, 11
	v_bitop3_b32 v7, v7, v8, 28 bitop3:0x6c
	v_lshl_add_u32 v7, v7, 2, v40
	ds_add_u32 v7, v9
	s_or_b64 exec, exec, s[0:1]
	s_cmpk_lt_i32 s77, 0xe0
	s_cbranch_scc0 .LBB0_1690

.LBB0_1549:
	v_lshrrev_b32_e32 v7, 21, v53
	s_waitcnt lgkmcnt(0)
	v_cmp_eq_u32_e32 vcc, v7, v6
	s_and_saveexec_b64 s[0:1], vcc
	v_lshrrev_b32_e32 v7, 13, v53
	v_bfe_u32 v8, v53, 10, 11
	v_bitop3_b32 v7, v7, v8, 28 bitop3:0x6c
	v_lshl_add_u32 v7, v7, 2, v40
	ds_add_u32 v7, v9
	s_or_b64 exec, exec, s[0:1]
	v_lshrrev_b32_e32 v7, 21, v52
	v_cmp_eq_u32_e32 vcc, v7, v6
	s_and_saveexec_b64 s[0:1], vcc
	v_lshrrev_b32_e32 v7, 13, v52
	v_bfe_u32 v8, v52, 10, 11
	v_bitop3_b32 v7, v7, v8, 28 bitop3:0x6c
	v_lshl_add_u32 v7, v7, 2, v40
	ds_add_u32 v7, v9
	s_or_b64 exec, exec, s[0:1]
	v_lshrrev_b32_e32 v7, 21, v51
	v_cmp_eq_u32_e32 vcc, v7, v6
	s_and_saveexec_b64 s[0:1], vcc
	v_lshrrev_b32_e32 v7, 13, v51
	v_bfe_u32 v8, v51, 10, 11
	v_bitop3_b32 v7, v7, v8, 28 bitop3:0x6c
	v_lshl_add_u32 v7, v7, 2, v40
	ds_add_u32 v7, v9
	s_or_b64 exec, exec, s[0:1]
	v_lshrrev_b32_e32 v7, 21, v50
	v_cmp_eq_u32_e32 vcc, v7, v6
	s_and_saveexec_b64 s[0:1], vcc
	v_lshrrev_b32_e32 v7, 13, v50
	v_bfe_u32 v8, v50, 10, 11
	v_bitop3_b32 v7, v7, v8, 28 bitop3:0x6c
	v_lshl_add_u32 v7, v7, 2, v40
	ds_add_u32 v7, v9
	s_or_b64 exec, exec, s[0:1]
	s_cmpk_lt_i32 s77, 0xf0
	s_cbranch_scc0 .LBB0_1700

.LBB0_1560:
	v_lshrrev_b32_e32 v7, 21, v162
	s_waitcnt lgkmcnt(0)
	v_cmp_eq_u32_e32 vcc, v7, v6
	s_and_saveexec_b64 s[0:1], vcc
	v_lshrrev_b32_e32 v7, 13, v162
	v_bfe_u32 v8, v162, 10, 11
	v_bitop3_b32 v7, v7, v8, 28 bitop3:0x6c
	v_lshl_add_u32 v7, v7, 2, v40
	ds_add_u32 v7, v9
	s_or_b64 exec, exec, s[0:1]
	v_lshrrev_b32_e32 v7, 21, v161
	v_cmp_eq_u32_e32 vcc, v7, v6
	s_and_saveexec_b64 s[0:1], vcc
	v_lshrrev_b32_e32 v7, 13, v161
	v_bfe_u32 v8, v161, 10, 11
	v_bitop3_b32 v7, v7, v8, 28 bitop3:0x6c
	v_lshl_add_u32 v7, v7, 2, v40
	ds_add_u32 v7, v9
	s_or_b64 exec, exec, s[0:1]
	v_lshrrev_b32_e32 v7, 21, v160
	v_cmp_eq_u32_e32 vcc, v7, v6
	s_and_saveexec_b64 s[0:1], vcc
	v_lshrrev_b32_e32 v7, 13, v160
	v_bfe_u32 v8, v160, 10, 11
	v_bitop3_b32 v7, v7, v8, 28 bitop3:0x6c
	v_lshl_add_u32 v7, v7, 2, v40
	ds_add_u32 v7, v9
	s_or_b64 exec, exec, s[0:1]
	v_lshrrev_b32_e32 v7, 21, v159
	v_cmp_eq_u32_e32 vcc, v7, v6
	s_and_saveexec_b64 s[0:1], vcc
	v_lshrrev_b32_e32 v7, 13, v159
	v_bfe_u32 v8, v159, 10, 11
	v_bitop3_b32 v7, v7, v8, 28 bitop3:0x6c
	v_lshl_add_u32 v7, v7, 2, v40
	ds_add_u32 v7, v9
	s_or_b64 exec, exec, s[0:1]
	s_cmp_lt_i32 s77, 24
	s_cbranch_scc0 .LBB0_1419

.LBB0_1570:
	v_lshrrev_b32_e32 v7, 21, v154
	s_waitcnt lgkmcnt(0)
	v_cmp_eq_u32_e32 vcc, v7, v6
	s_and_saveexec_b64 s[0:1], vcc
	v_lshrrev_b32_e32 v7, 13, v154
	v_bfe_u32 v8, v154, 10, 11
	v_bitop3_b32 v7, v7, v8, 28 bitop3:0x6c
	v_lshl_add_u32 v7, v7, 2, v40
	ds_add_u32 v7, v9
	s_or_b64 exec, exec, s[0:1]
	v_lshrrev_b32_e32 v7, 21, v153
	v_cmp_eq_u32_e32 vcc, v7, v6
	s_and_saveexec_b64 s[0:1], vcc
	v_lshrrev_b32_e32 v7, 13, v153
	v_bfe_u32 v8, v153, 10, 11
	v_bitop3_b32 v7, v7, v8, 28 bitop3:0x6c
	v_lshl_add_u32 v7, v7, 2, v40
	ds_add_u32 v7, v9
	s_or_b64 exec, exec, s[0:1]
	v_lshrrev_b32_e32 v7, 21, v152
	v_cmp_eq_u32_e32 vcc, v7, v6
	s_and_saveexec_b64 s[0:1], vcc
	v_lshrrev_b32_e32 v7, 13, v152
	v_bfe_u32 v8, v152, 10, 11
	v_bitop3_b32 v7, v7, v8, 28 bitop3:0x6c
	v_lshl_add_u32 v7, v7, 2, v40
	ds_add_u32 v7, v9
	s_or_b64 exec, exec, s[0:1]
	v_lshrrev_b32_e32 v7, 21, v151
	v_cmp_eq_u32_e32 vcc, v7, v6
	s_and_saveexec_b64 s[0:1], vcc
	v_lshrrev_b32_e32 v7, 13, v151
	v_bfe_u32 v8, v151, 10, 11
	v_bitop3_b32 v7, v7, v8, 28 bitop3:0x6c
	v_lshl_add_u32 v7, v7, 2, v40
	ds_add_u32 v7, v9
	s_or_b64 exec, exec, s[0:1]
	s_cmp_lt_i32 s77, 40
	s_cbranch_scc0 .LBB0_1429

.LBB0_1580:
	v_lshrrev_b32_e32 v7, 21, v146
	s_waitcnt lgkmcnt(0)
	v_cmp_eq_u32_e32 vcc, v7, v6
	s_and_saveexec_b64 s[0:1], vcc
	v_lshrrev_b32_e32 v7, 13, v146
	v_bfe_u32 v8, v146, 10, 11
	v_bitop3_b32 v7, v7, v8, 28 bitop3:0x6c
	v_lshl_add_u32 v7, v7, 2, v40
	ds_add_u32 v7, v9
	s_or_b64 exec, exec, s[0:1]
	v_lshrrev_b32_e32 v7, 21, v145
	v_cmp_eq_u32_e32 vcc, v7, v6
	s_and_saveexec_b64 s[0:1], vcc
	v_lshrrev_b32_e32 v7, 13, v145
	v_bfe_u32 v8, v145, 10, 11
	v_bitop3_b32 v7, v7, v8, 28 bitop3:0x6c
	v_lshl_add_u32 v7, v7, 2, v40
	ds_add_u32 v7, v9
	s_or_b64 exec, exec, s[0:1]
	v_lshrrev_b32_e32 v7, 21, v144
	v_cmp_eq_u32_e32 vcc, v7, v6
	s_and_saveexec_b64 s[0:1], vcc
	v_lshrrev_b32_e32 v7, 13, v144
	v_bfe_u32 v8, v144, 10, 11
	v_bitop3_b32 v7, v7, v8, 28 bitop3:0x6c
	v_lshl_add_u32 v7, v7, 2, v40
	ds_add_u32 v7, v9
	s_or_b64 exec, exec, s[0:1]
	v_lshrrev_b32_e32 v7, 21, v143
	v_cmp_eq_u32_e32 vcc, v7, v6
	s_and_saveexec_b64 s[0:1], vcc
	v_lshrrev_b32_e32 v7, 13, v143
	v_bfe_u32 v8, v143, 10, 11
	v_bitop3_b32 v7, v7, v8, 28 bitop3:0x6c
	v_lshl_add_u32 v7, v7, 2, v40
	ds_add_u32 v7, v9
	s_or_b64 exec, exec, s[0:1]
	s_cmp_lt_i32 s77, 56
	s_cbranch_scc0 .LBB0_1439

.LBB0_1590:
	v_lshrrev_b32_e32 v7, 21, v138
	s_waitcnt lgkmcnt(0)
	v_cmp_eq_u32_e32 vcc, v7, v6
	s_and_saveexec_b64 s[0:1], vcc
	v_lshrrev_b32_e32 v7, 13, v138
	v_bfe_u32 v8, v138, 10, 11
	v_bitop3_b32 v7, v7, v8, 28 bitop3:0x6c
	v_lshl_add_u32 v7, v7, 2, v40
	ds_add_u32 v7, v9
	s_or_b64 exec, exec, s[0:1]
	v_lshrrev_b32_e32 v7, 21, v137
	v_cmp_eq_u32_e32 vcc, v7, v6
	s_and_saveexec_b64 s[0:1], vcc
	v_lshrrev_b32_e32 v7, 13, v137
	v_bfe_u32 v8, v137, 10, 11
	v_bitop3_b32 v7, v7, v8, 28 bitop3:0x6c
	v_lshl_add_u32 v7, v7, 2, v40
	ds_add_u32 v7, v9
	s_or_b64 exec, exec, s[0:1]
	v_lshrrev_b32_e32 v7, 21, v136
	v_cmp_eq_u32_e32 vcc, v7, v6
	s_and_saveexec_b64 s[0:1], vcc
	v_lshrrev_b32_e32 v7, 13, v136
	v_bfe_u32 v8, v136, 10, 11
	v_bitop3_b32 v7, v7, v8, 28 bitop3:0x6c
	v_lshl_add_u32 v7, v7, 2, v40
	ds_add_u32 v7, v9
	s_or_b64 exec, exec, s[0:1]
	v_lshrrev_b32_e32 v7, 21, v135
	v_cmp_eq_u32_e32 vcc, v7, v6
	s_and_saveexec_b64 s[0:1], vcc
	v_lshrrev_b32_e32 v7, 13, v135
	v_bfe_u32 v8, v135, 10, 11
	v_bitop3_b32 v7, v7, v8, 28 bitop3:0x6c
	v_lshl_add_u32 v7, v7, 2, v40
	ds_add_u32 v7, v9
	s_or_b64 exec, exec, s[0:1]
	s_cmpk_lt_i32 s77, 0x48
	s_cbranch_scc0 .LBB0_1449

.LBB0_1600:
	v_lshrrev_b32_e32 v7, 21, v130
	s_waitcnt lgkmcnt(0)
	v_cmp_eq_u32_e32 vcc, v7, v6
	s_and_saveexec_b64 s[0:1], vcc
	v_lshrrev_b32_e32 v7, 13, v130
	v_bfe_u32 v8, v130, 10, 11
	v_bitop3_b32 v7, v7, v8, 28 bitop3:0x6c
	v_lshl_add_u32 v7, v7, 2, v40
	ds_add_u32 v7, v9
	s_or_b64 exec, exec, s[0:1]
	v_lshrrev_b32_e32 v7, 21, v129
	v_cmp_eq_u32_e32 vcc, v7, v6
	s_and_saveexec_b64 s[0:1], vcc
	v_lshrrev_b32_e32 v7, 13, v129
	v_bfe_u32 v8, v129, 10, 11
	v_bitop3_b32 v7, v7, v8, 28 bitop3:0x6c
	v_lshl_add_u32 v7, v7, 2, v40
	ds_add_u32 v7, v9
	s_or_b64 exec, exec, s[0:1]
	v_lshrrev_b32_e32 v7, 21, v128
	v_cmp_eq_u32_e32 vcc, v7, v6
	s_and_saveexec_b64 s[0:1], vcc
	v_lshrrev_b32_e32 v7, 13, v128
	v_bfe_u32 v8, v128, 10, 11
	v_bitop3_b32 v7, v7, v8, 28 bitop3:0x6c
	v_lshl_add_u32 v7, v7, 2, v40
	ds_add_u32 v7, v9
	s_or_b64 exec, exec, s[0:1]
	v_lshrrev_b32_e32 v7, 21, v127
	v_cmp_eq_u32_e32 vcc, v7, v6
	s_and_saveexec_b64 s[0:1], vcc
	v_lshrrev_b32_e32 v7, 13, v127
	v_bfe_u32 v8, v127, 10, 11
	v_bitop3_b32 v7, v7, v8, 28 bitop3:0x6c
	v_lshl_add_u32 v7, v7, 2, v40
	ds_add_u32 v7, v9
	s_or_b64 exec, exec, s[0:1]
	s_cmpk_lt_i32 s77, 0x58
	s_cbranch_scc0 .LBB0_1459

.LBB0_1610:
	v_lshrrev_b32_e32 v7, 21, v122
	s_waitcnt lgkmcnt(0)
	v_cmp_eq_u32_e32 vcc, v7, v6
	s_and_saveexec_b64 s[0:1], vcc
	v_lshrrev_b32_e32 v7, 13, v122
	v_bfe_u32 v8, v122, 10, 11
	v_bitop3_b32 v7, v7, v8, 28 bitop3:0x6c
	v_lshl_add_u32 v7, v7, 2, v40
	ds_add_u32 v7, v9
	s_or_b64 exec, exec, s[0:1]
	v_lshrrev_b32_e32 v7, 21, v121
	v_cmp_eq_u32_e32 vcc, v7, v6
	s_and_saveexec_b64 s[0:1], vcc
	v_lshrrev_b32_e32 v7, 13, v121
	v_bfe_u32 v8, v121, 10, 11
	v_bitop3_b32 v7, v7, v8, 28 bitop3:0x6c
	v_lshl_add_u32 v7, v7, 2, v40
	ds_add_u32 v7, v9
	s_or_b64 exec, exec, s[0:1]
	v_lshrrev_b32_e32 v7, 21, v120
	v_cmp_eq_u32_e32 vcc, v7, v6
	s_and_saveexec_b64 s[0:1], vcc
	v_lshrrev_b32_e32 v7, 13, v120
	v_bfe_u32 v8, v120, 10, 11
	v_bitop3_b32 v7, v7, v8, 28 bitop3:0x6c
	v_lshl_add_u32 v7, v7, 2, v40
	ds_add_u32 v7, v9
	s_or_b64 exec, exec, s[0:1]
	v_lshrrev_b32_e32 v7, 21, v119
	v_cmp_eq_u32_e32 vcc, v7, v6
	s_and_saveexec_b64 s[0:1], vcc
	v_lshrrev_b32_e32 v7, 13, v119
	v_bfe_u32 v8, v119, 10, 11
	v_bitop3_b32 v7, v7, v8, 28 bitop3:0x6c
	v_lshl_add_u32 v7, v7, 2, v40
	ds_add_u32 v7, v9
	s_or_b64 exec, exec, s[0:1]
	s_cmpk_lt_i32 s77, 0x68
	s_cbranch_scc0 .LBB0_1469

.LBB0_1620:
	v_lshrrev_b32_e32 v7, 21, v113
	s_waitcnt lgkmcnt(0)
	v_cmp_eq_u32_e32 vcc, v7, v6
	s_and_saveexec_b64 s[0:1], vcc
	v_lshrrev_b32_e32 v7, 13, v113
	v_bfe_u32 v8, v113, 10, 11
	v_bitop3_b32 v7, v7, v8, 28 bitop3:0x6c
	v_lshl_add_u32 v7, v7, 2, v40
	ds_add_u32 v7, v9
	s_or_b64 exec, exec, s[0:1]
	v_lshrrev_b32_e32 v7, 21, v112
	v_cmp_eq_u32_e32 vcc, v7, v6
	s_and_saveexec_b64 s[0:1], vcc
	v_lshrrev_b32_e32 v7, 13, v112
	v_bfe_u32 v8, v112, 10, 11
	v_bitop3_b32 v7, v7, v8, 28 bitop3:0x6c
	v_lshl_add_u32 v7, v7, 2, v40
	ds_add_u32 v7, v9
	s_or_b64 exec, exec, s[0:1]
	v_lshrrev_b32_e32 v7, 21, v111
	v_cmp_eq_u32_e32 vcc, v7, v6
	s_and_saveexec_b64 s[0:1], vcc
	v_lshrrev_b32_e32 v7, 13, v111
	v_bfe_u32 v8, v111, 10, 11
	v_bitop3_b32 v7, v7, v8, 28 bitop3:0x6c
	v_lshl_add_u32 v7, v7, 2, v40
	ds_add_u32 v7, v9
	s_or_b64 exec, exec, s[0:1]
	v_lshrrev_b32_e32 v7, 21, v110
	v_cmp_eq_u32_e32 vcc, v7, v6
	s_and_saveexec_b64 s[0:1], vcc
	v_lshrrev_b32_e32 v7, 13, v110
	v_bfe_u32 v8, v110, 10, 11
	v_bitop3_b32 v7, v7, v8, 28 bitop3:0x6c
	v_lshl_add_u32 v7, v7, 2, v40
	ds_add_u32 v7, v9
	s_or_b64 exec, exec, s[0:1]
	s_cmpk_lt_i32 s77, 0x78
	s_cbranch_scc0 .LBB0_1479

.LBB0_1630:
	v_lshrrev_b32_e32 v7, 21, v106
	s_waitcnt lgkmcnt(0)
	v_cmp_eq_u32_e32 vcc, v7, v6
	s_and_saveexec_b64 s[0:1], vcc
	v_lshrrev_b32_e32 v7, 13, v106
	v_bfe_u32 v8, v106, 10, 11
	v_bitop3_b32 v7, v7, v8, 28 bitop3:0x6c
	v_lshl_add_u32 v7, v7, 2, v40
	ds_add_u32 v7, v9
	s_or_b64 exec, exec, s[0:1]
	v_lshrrev_b32_e32 v7, 21, v104
	v_cmp_eq_u32_e32 vcc, v7, v6
	s_and_saveexec_b64 s[0:1], vcc
	v_lshrrev_b32_e32 v7, 13, v104
	v_bfe_u32 v8, v104, 10, 11
	v_bitop3_b32 v7, v7, v8, 28 bitop3:0x6c
	v_lshl_add_u32 v7, v7, 2, v40
	ds_add_u32 v7, v9
	s_or_b64 exec, exec, s[0:1]
	v_lshrrev_b32_e32 v7, 21, v103
	v_cmp_eq_u32_e32 vcc, v7, v6
	s_and_saveexec_b64 s[0:1], vcc
	v_lshrrev_b32_e32 v7, 13, v103
	v_bfe_u32 v8, v103, 10, 11
	v_bitop3_b32 v7, v7, v8, 28 bitop3:0x6c
	v_lshl_add_u32 v7, v7, 2, v40
	ds_add_u32 v7, v9
	s_or_b64 exec, exec, s[0:1]
	v_lshrrev_b32_e32 v7, 21, v102
	v_cmp_eq_u32_e32 vcc, v7, v6
	s_and_saveexec_b64 s[0:1], vcc
	v_lshrrev_b32_e32 v7, 13, v102
	v_bfe_u32 v8, v102, 10, 11
	v_bitop3_b32 v7, v7, v8, 28 bitop3:0x6c
	v_lshl_add_u32 v7, v7, 2, v40
	ds_add_u32 v7, v9
	s_or_b64 exec, exec, s[0:1]
	s_cmpk_lt_i32 s77, 0x88
	s_cbranch_scc0 .LBB0_1489

.LBB0_1640:
	v_lshrrev_b32_e32 v7, 21, v97
	s_waitcnt lgkmcnt(0)
	v_cmp_eq_u32_e32 vcc, v7, v6
	s_and_saveexec_b64 s[0:1], vcc
	v_lshrrev_b32_e32 v7, 13, v97
	v_bfe_u32 v8, v97, 10, 11
	v_bitop3_b32 v7, v7, v8, 28 bitop3:0x6c
	v_lshl_add_u32 v7, v7, 2, v40
	ds_add_u32 v7, v9
	s_or_b64 exec, exec, s[0:1]
	v_lshrrev_b32_e32 v7, 21, v96
	v_cmp_eq_u32_e32 vcc, v7, v6
	s_and_saveexec_b64 s[0:1], vcc
	v_lshrrev_b32_e32 v7, 13, v96
	v_bfe_u32 v8, v96, 10, 11
	v_bitop3_b32 v7, v7, v8, 28 bitop3:0x6c
	v_lshl_add_u32 v7, v7, 2, v40
	ds_add_u32 v7, v9
	s_or_b64 exec, exec, s[0:1]
	v_lshrrev_b32_e32 v7, 21, v95
	v_cmp_eq_u32_e32 vcc, v7, v6
	s_and_saveexec_b64 s[0:1], vcc
	v_lshrrev_b32_e32 v7, 13, v95
	v_bfe_u32 v8, v95, 10, 11
	v_bitop3_b32 v7, v7, v8, 28 bitop3:0x6c
	v_lshl_add_u32 v7, v7, 2, v40
	ds_add_u32 v7, v9
	s_or_b64 exec, exec, s[0:1]
	v_lshrrev_b32_e32 v7, 21, v94
	v_cmp_eq_u32_e32 vcc, v7, v6
	s_and_saveexec_b64 s[0:1], vcc
	v_lshrrev_b32_e32 v7, 13, v94
	v_bfe_u32 v8, v94, 10, 11
	v_bitop3_b32 v7, v7, v8, 28 bitop3:0x6c
	v_lshl_add_u32 v7, v7, 2, v40
	ds_add_u32 v7, v9
	s_or_b64 exec, exec, s[0:1]
	s_cmpk_lt_i32 s77, 0x98
	s_cbranch_scc0 .LBB0_1499

.LBB0_1650:
	v_lshrrev_b32_e32 v7, 21, v89
	s_waitcnt lgkmcnt(0)
	v_cmp_eq_u32_e32 vcc, v7, v6
	s_and_saveexec_b64 s[0:1], vcc
	v_lshrrev_b32_e32 v7, 13, v89
	v_bfe_u32 v8, v89, 10, 11
	v_bitop3_b32 v7, v7, v8, 28 bitop3:0x6c
	v_lshl_add_u32 v7, v7, 2, v40
	ds_add_u32 v7, v9
	s_or_b64 exec, exec, s[0:1]
	v_lshrrev_b32_e32 v7, 21, v88
	v_cmp_eq_u32_e32 vcc, v7, v6
	s_and_saveexec_b64 s[0:1], vcc
	v_lshrrev_b32_e32 v7, 13, v88
	v_bfe_u32 v8, v88, 10, 11
	v_bitop3_b32 v7, v7, v8, 28 bitop3:0x6c
	v_lshl_add_u32 v7, v7, 2, v40
	ds_add_u32 v7, v9
	s_or_b64 exec, exec, s[0:1]
	v_lshrrev_b32_e32 v7, 21, v87
	v_cmp_eq_u32_e32 vcc, v7, v6
	s_and_saveexec_b64 s[0:1], vcc
	v_lshrrev_b32_e32 v7, 13, v87
	v_bfe_u32 v8, v87, 10, 11
	v_bitop3_b32 v7, v7, v8, 28 bitop3:0x6c
	v_lshl_add_u32 v7, v7, 2, v40
	ds_add_u32 v7, v9
	s_or_b64 exec, exec, s[0:1]
	v_lshrrev_b32_e32 v7, 21, v86
	v_cmp_eq_u32_e32 vcc, v7, v6
	s_and_saveexec_b64 s[0:1], vcc
	v_lshrrev_b32_e32 v7, 13, v86
	v_bfe_u32 v8, v86, 10, 11
	v_bitop3_b32 v7, v7, v8, 28 bitop3:0x6c
	v_lshl_add_u32 v7, v7, 2, v40
	ds_add_u32 v7, v9
	s_or_b64 exec, exec, s[0:1]
	s_cmpk_lt_i32 s77, 0xa8
	s_cbranch_scc0 .LBB0_1509

.LBB0_1660:
	v_lshrrev_b32_e32 v7, 21, v81
	s_waitcnt lgkmcnt(0)
	v_cmp_eq_u32_e32 vcc, v7, v6
	s_and_saveexec_b64 s[0:1], vcc
	v_lshrrev_b32_e32 v7, 13, v81
	v_bfe_u32 v8, v81, 10, 11
	v_bitop3_b32 v7, v7, v8, 28 bitop3:0x6c
	v_lshl_add_u32 v7, v7, 2, v40
	ds_add_u32 v7, v9
	s_or_b64 exec, exec, s[0:1]
	v_lshrrev_b32_e32 v7, 21, v80
	v_cmp_eq_u32_e32 vcc, v7, v6
	s_and_saveexec_b64 s[0:1], vcc
	v_lshrrev_b32_e32 v7, 13, v80
	v_bfe_u32 v8, v80, 10, 11
	v_bitop3_b32 v7, v7, v8, 28 bitop3:0x6c
	v_lshl_add_u32 v7, v7, 2, v40
	ds_add_u32 v7, v9
	s_or_b64 exec, exec, s[0:1]
	v_lshrrev_b32_e32 v7, 21, v79
	v_cmp_eq_u32_e32 vcc, v7, v6
	s_and_saveexec_b64 s[0:1], vcc
	v_lshrrev_b32_e32 v7, 13, v79
	v_bfe_u32 v8, v79, 10, 11
	v_bitop3_b32 v7, v7, v8, 28 bitop3:0x6c
	v_lshl_add_u32 v7, v7, 2, v40
	ds_add_u32 v7, v9
	s_or_b64 exec, exec, s[0:1]
	v_lshrrev_b32_e32 v7, 21, v78
	v_cmp_eq_u32_e32 vcc, v7, v6
	s_and_saveexec_b64 s[0:1], vcc
	v_lshrrev_b32_e32 v7, 13, v78
	v_bfe_u32 v8, v78, 10, 11
	v_bitop3_b32 v7, v7, v8, 28 bitop3:0x6c
	v_lshl_add_u32 v7, v7, 2, v40
	ds_add_u32 v7, v9
	s_or_b64 exec, exec, s[0:1]
	s_cmpk_lt_i32 s77, 0xb8
	s_cbranch_scc0 .LBB0_1519

.LBB0_1670:
	v_lshrrev_b32_e32 v7, 21, v73
	s_waitcnt lgkmcnt(0)
	v_cmp_eq_u32_e32 vcc, v7, v6
	s_and_saveexec_b64 s[0:1], vcc
	v_lshrrev_b32_e32 v7, 13, v73
	v_bfe_u32 v8, v73, 10, 11
	v_bitop3_b32 v7, v7, v8, 28 bitop3:0x6c
	v_lshl_add_u32 v7, v7, 2, v40
	ds_add_u32 v7, v9
	s_or_b64 exec, exec, s[0:1]
	v_lshrrev_b32_e32 v7, 21, v72
	v_cmp_eq_u32_e32 vcc, v7, v6
	s_and_saveexec_b64 s[0:1], vcc
	v_lshrrev_b32_e32 v7, 13, v72
	v_bfe_u32 v8, v72, 10, 11
	v_bitop3_b32 v7, v7, v8, 28 bitop3:0x6c
	v_lshl_add_u32 v7, v7, 2, v40
	ds_add_u32 v7, v9
	s_or_b64 exec, exec, s[0:1]
	v_lshrrev_b32_e32 v7, 21, v71
	v_cmp_eq_u32_e32 vcc, v7, v6
	s_and_saveexec_b64 s[0:1], vcc
	v_lshrrev_b32_e32 v7, 13, v71
	v_bfe_u32 v8, v71, 10, 11
	v_bitop3_b32 v7, v7, v8, 28 bitop3:0x6c
	v_lshl_add_u32 v7, v7, 2, v40
	ds_add_u32 v7, v9
	s_or_b64 exec, exec, s[0:1]
	v_lshrrev_b32_e32 v7, 21, v70
	v_cmp_eq_u32_e32 vcc, v7, v6
	s_and_saveexec_b64 s[0:1], vcc
	v_lshrrev_b32_e32 v7, 13, v70
	v_bfe_u32 v8, v70, 10, 11
	v_bitop3_b32 v7, v7, v8, 28 bitop3:0x6c
	v_lshl_add_u32 v7, v7, 2, v40
	ds_add_u32 v7, v9
	s_or_b64 exec, exec, s[0:1]
	s_cmpk_lt_i32 s77, 0xc8
	s_cbranch_scc0 .LBB0_1529

.LBB0_1680:
	v_lshrrev_b32_e32 v7, 21, v65
	s_waitcnt lgkmcnt(0)
	v_cmp_eq_u32_e32 vcc, v7, v6
	s_and_saveexec_b64 s[0:1], vcc
	v_lshrrev_b32_e32 v7, 13, v65
	v_bfe_u32 v8, v65, 10, 11
	v_bitop3_b32 v7, v7, v8, 28 bitop3:0x6c
	v_lshl_add_u32 v7, v7, 2, v40
	ds_add_u32 v7, v9
	s_or_b64 exec, exec, s[0:1]
	v_lshrrev_b32_e32 v7, 21, v64
	v_cmp_eq_u32_e32 vcc, v7, v6
	s_and_saveexec_b64 s[0:1], vcc
	v_lshrrev_b32_e32 v7, 13, v64
	v_bfe_u32 v8, v64, 10, 11
	v_bitop3_b32 v7, v7, v8, 28 bitop3:0x6c
	v_lshl_add_u32 v7, v7, 2, v40
	ds_add_u32 v7, v9
	s_or_b64 exec, exec, s[0:1]
	v_lshrrev_b32_e32 v7, 21, v63
	v_cmp_eq_u32_e32 vcc, v7, v6
	s_and_saveexec_b64 s[0:1], vcc
	v_lshrrev_b32_e32 v7, 13, v63
	v_bfe_u32 v8, v63, 10, 11
	v_bitop3_b32 v7, v7, v8, 28 bitop3:0x6c
	v_lshl_add_u32 v7, v7, 2, v40
	ds_add_u32 v7, v9
	s_or_b64 exec, exec, s[0:1]
	v_lshrrev_b32_e32 v7, 21, v62
	v_cmp_eq_u32_e32 vcc, v7, v6
	s_and_saveexec_b64 s[0:1], vcc
	v_lshrrev_b32_e32 v7, 13, v62
	v_bfe_u32 v8, v62, 10, 11
	v_bitop3_b32 v7, v7, v8, 28 bitop3:0x6c
	v_lshl_add_u32 v7, v7, 2, v40
	ds_add_u32 v7, v9
	s_or_b64 exec, exec, s[0:1]
	s_cmpk_lt_i32 s77, 0xd8
	s_cbranch_scc0 .LBB0_1539

.LBB0_1690:
	v_lshrrev_b32_e32 v7, 21, v57
	s_waitcnt lgkmcnt(0)
	v_cmp_eq_u32_e32 vcc, v7, v6
	s_and_saveexec_b64 s[0:1], vcc
	v_lshrrev_b32_e32 v7, 13, v57
	v_bfe_u32 v8, v57, 10, 11
	v_bitop3_b32 v7, v7, v8, 28 bitop3:0x6c
	v_lshl_add_u32 v7, v7, 2, v40
	ds_add_u32 v7, v9
	s_or_b64 exec, exec, s[0:1]
	v_lshrrev_b32_e32 v7, 21, v56
	v_cmp_eq_u32_e32 vcc, v7, v6
	s_and_saveexec_b64 s[0:1], vcc
	v_lshrrev_b32_e32 v7, 13, v56
	v_bfe_u32 v8, v56, 10, 11
	v_bitop3_b32 v7, v7, v8, 28 bitop3:0x6c
	v_lshl_add_u32 v7, v7, 2, v40
	ds_add_u32 v7, v9
	s_or_b64 exec, exec, s[0:1]
	v_lshrrev_b32_e32 v7, 21, v55
	v_cmp_eq_u32_e32 vcc, v7, v6
	s_and_saveexec_b64 s[0:1], vcc
	v_lshrrev_b32_e32 v7, 13, v55
	v_bfe_u32 v8, v55, 10, 11
	v_bitop3_b32 v7, v7, v8, 28 bitop3:0x6c
	v_lshl_add_u32 v7, v7, 2, v40
	ds_add_u32 v7, v9
	s_or_b64 exec, exec, s[0:1]
	v_lshrrev_b32_e32 v7, 21, v54
	v_cmp_eq_u32_e32 vcc, v7, v6
	s_and_saveexec_b64 s[0:1], vcc
	v_lshrrev_b32_e32 v7, 13, v54
	v_bfe_u32 v8, v54, 10, 11
	v_bitop3_b32 v7, v7, v8, 28 bitop3:0x6c
	v_lshl_add_u32 v7, v7, 2, v40
	ds_add_u32 v7, v9
	s_or_b64 exec, exec, s[0:1]
	s_cmpk_lt_i32 s77, 0xe8
	s_cbranch_scc0 .LBB0_1549

.LBB0_1700:
	v_lshrrev_b32_e32 v7, 21, v49
	s_waitcnt lgkmcnt(0)
	v_cmp_eq_u32_e32 vcc, v7, v6
	s_and_saveexec_b64 s[0:1], vcc
	v_lshrrev_b32_e32 v7, 13, v49
	v_bfe_u32 v8, v49, 10, 11
	v_bitop3_b32 v7, v7, v8, 28 bitop3:0x6c
	v_lshl_add_u32 v7, v7, 2, v40
	ds_add_u32 v7, v9
	s_or_b64 exec, exec, s[0:1]
	v_lshrrev_b32_e32 v7, 21, v48
	v_cmp_eq_u32_e32 vcc, v7, v6
	s_and_saveexec_b64 s[0:1], vcc
	v_lshrrev_b32_e32 v7, 13, v48
	v_bfe_u32 v8, v48, 10, 11
	v_bitop3_b32 v7, v7, v8, 28 bitop3:0x6c
	v_lshl_add_u32 v7, v7, 2, v40
	ds_add_u32 v7, v9
	s_or_b64 exec, exec, s[0:1]
	v_lshrrev_b32_e32 v7, 21, v47
	v_cmp_eq_u32_e32 vcc, v7, v6
	s_and_saveexec_b64 s[0:1], vcc
	v_lshrrev_b32_e32 v7, 13, v47
	v_bfe_u32 v8, v47, 10, 11
	v_bitop3_b32 v7, v7, v8, 28 bitop3:0x6c
	v_lshl_add_u32 v7, v7, 2, v40
	ds_add_u32 v7, v9
	s_or_b64 exec, exec, s[0:1]
	v_lshrrev_b32_e32 v7, 21, v46
	v_cmp_eq_u32_e32 vcc, v7, v6
	s_and_saveexec_b64 s[0:1], vcc
	v_lshrrev_b32_e32 v7, 13, v46
	v_bfe_u32 v8, v46, 10, 11
	v_bitop3_b32 v7, v7, v8, 28 bitop3:0x6c
	v_lshl_add_u32 v7, v7, 2, v40
	ds_add_u32 v7, v9
	s_or_b64 exec, exec, s[0:1]
	s_cmpk_lt_i32 s77, 0xf8
	s_cbranch_scc1 .LBB0_1717
.LBB0_1709:
	v_lshrrev_b32_e32 v7, 21, v45
	s_waitcnt lgkmcnt(0)
	v_cmp_eq_u32_e32 vcc, v7, v6
	s_and_saveexec_b64 s[0:1], vcc
	v_lshrrev_b32_e32 v7, 13, v45
	v_bfe_u32 v8, v45, 10, 11
	v_bitop3_b32 v7, v7, v8, 28 bitop3:0x6c
	v_lshl_add_u32 v7, v7, 2, v40
	ds_add_u32 v7, v9
	s_or_b64 exec, exec, s[0:1]
	v_lshrrev_b32_e32 v7, 21, v44
	v_cmp_eq_u32_e32 vcc, v7, v6
	s_and_saveexec_b64 s[0:1], vcc
	v_lshrrev_b32_e32 v7, 13, v44
	v_bfe_u32 v8, v44, 10, 11
	v_bitop3_b32 v7, v7, v8, 28 bitop3:0x6c
	v_lshl_add_u32 v7, v7, 2, v40
	ds_add_u32 v7, v9
	s_or_b64 exec, exec, s[0:1]
	v_lshrrev_b32_e32 v7, 21, v43
	v_cmp_eq_u32_e32 vcc, v7, v6
	s_and_saveexec_b64 s[0:1], vcc
	v_lshrrev_b32_e32 v7, 13, v43
	v_bfe_u32 v8, v43, 10, 11
	v_bitop3_b32 v7, v7, v8, 28 bitop3:0x6c
	v_lshl_add_u32 v7, v7, 2, v40
	ds_add_u32 v7, v9
	s_or_b64 exec, exec, s[0:1]
	v_lshrrev_b32_e32 v7, 21, v42
	v_cmp_eq_u32_e32 vcc, v7, v6
	s_and_b64 exec, exec, vcc
	v_lshrrev_b32_e32 v6, 13, v42
	v_bfe_u32 v7, v42, 10, 11
	v_bitop3_b32 v6, v6, v7, 28 bitop3:0x6c
	v_lshl_add_u32 v6, v6, 2, v40
	ds_add_u32 v6, v9

.LBB0_1720:
	s_or_b32 s8, s8, s26
	s_lshl_b32 s9, s8, 4
	s_add_i32 s10, s9, 0
	s_add_i32 s9, s10, 0x22008
	v_mov_b32_e32 v15, s9
	ds_read_b32 v15, v15
	s_waitcnt lgkmcnt(0)
	v_cmp_eq_u32_e32 vcc, 0, v15
	s_cbranch_vccnz .LBB0_1719
	s_lshl_b32 s11, s8, 13
	s_add_i32 s9, s10, 0x22004
	s_add_i32 s8, s11, 0
	v_mov_b32_e32 v15, s9
	v_add3_u32 v16, s8, v13, v14
	v_lshl_add_u32 v20, v6, 2, s8
	v_lshl_add_u32 v24, v7, 2, s8
	ds_read_b32 v15, v15
	ds_read_b128 v[16:19], v16
	ds_read_b128 v[20:23], v20
	ds_read_b128 v[24:27], v24
	v_lshl_add_u32 v28, v8, 2, s8
	v_lshl_add_u32 v32, v9, 2, s8
	v_lshl_add_u32 v173, v10, 2, s8
	v_lshl_add_u32 v178, v11, 2, s8
	ds_read_b128 v[28:31], v28
	ds_read_b128 v[32:35], v32
	ds_read_b128 v[174:177], v173
	ds_read_b128 v[178:181], v178
	v_lshl_add_u32 v173, v12, 2, s8
	ds_read_b128 v[182:185], v173
	s_waitcnt lgkmcnt(5)
	v_lshlrev_b32_e32 v15, 16, v15
	v_add_u32_e32 v188, v25, v24
	v_add3_u32 v173, v17, v16, v18
	v_add3_u32 v188, v188, v26, v27
	s_waitcnt lgkmcnt(3)
	v_add_u32_e32 v200, v33, v32
	s_waitcnt lgkmcnt(1)
	v_add_u32_e32 v201, v179, v178
	v_add3_u32 v173, v173, v19, v20
	v_add3_u32 v188, v188, v28, v29
	v_add3_u32 v200, v200, v34, v35
	v_add3_u32 v201, v201, v180, v181
	v_add3_u32 v173, v173, v21, v22
	v_add3_u32 v188, v188, v30, v31
	v_add3_u32 v200, v200, v174, v175
	s_waitcnt lgkmcnt(0)
	v_add3_u32 v201, v201, v182, v183
	v_add3_u32 v200, v200, v176, v177
	v_add3_u32 v201, v201, v184, v185
	v_add3_u32 v173, v173, v23, v188
	v_add3_u32 v173, v173, v200, v201
	s_nop 1
	v_add_u32_dpp v202, v173, v173 row_shr:1 row_mask:0xf bank_mask:0xf bound_ctrl:1
	s_nop 1
	v_add_u32_dpp v202, v202, v202 row_shr:2 row_mask:0xf bank_mask:0xf bound_ctrl:1
	s_nop 1
	v_add_u32_dpp v202, v202, v202 row_shr:4 row_mask:0xf bank_mask:0xf bound_ctrl:1
	s_nop 1
	v_add_u32_dpp v202, v202, v202 row_shr:8 row_mask:0xf bank_mask:0xf bound_ctrl:1
	s_nop 1
	v_add_u32_dpp v202, v202, v202 row_bcast:15 row_mask:0xa bank_mask:0xf
	s_nop 1
	v_add_u32_dpp v202, v202, v202 row_bcast:31 row_mask:0xc bank_mask:0xf
	v_sub_u32_e32 v173, v202, v173
	v_add_u32_e32 v201, v173, v201
	v_add_u32_e32 v200, v201, v200
	v_cmp_ge_u32_e32 vcc, v202, v15
	v_cmp_ge_u32_e64 s[44:45], v200, v15
	v_cmp_ge_u32_e64 s[46:47], v201, v15
	s_ff1_i32_b64 s14, vcc
	v_add_u32_e32 v188, v200, v188
	v_cmp_lt_u32_e32 vcc, v201, v15
	s_or_b64 s[8:9], s[46:47], s[44:45]
	v_cmp_lt_u32_e64 s[42:43], v188, v15
	s_xor_b64 s[12:13], s[8:9], -1
	s_and_b64 vcc, vcc, s[44:45]
	v_cndmask_b32_e64 v188, v200, v188, s[42:43]
	v_cndmask_b32_e64 v185, 0, v185, s[46:47]
	v_cndmask_b32_e32 v177, 0, v177, vcc
	s_or_b64 s[8:9], s[8:9], s[42:43]
	s_and_b64 s[48:49], s[12:13], s[42:43]
	v_cndmask_b32_e64 v188, v188, v201, s[44:45]
	v_or_b32_e32 v177, v177, v185
	v_cndmask_b32_e64 v31, v31, 0, s[8:9]
	v_cndmask_b32_e64 v23, 0, v23, s[48:49]
	v_cndmask_b32_e64 v173, v188, v173, s[46:47]
	v_or3_b32 v23, v177, v31, v23
	v_add_u32_e32 v23, v23, v173
	v_cmp_lt_u32_e64 s[50:51], v23, v15
	v_cndmask_b32_e32 v176, 0, v176, vcc
	v_cndmask_b32_e64 v30, v30, 0, s[8:9]
	v_cndmask_b32_e64 v31, v173, v23, s[50:51]
	v_cndmask_b32_e64 v173, 0, v184, s[46:47]
	v_or_b32_e32 v173, v176, v173
	v_cndmask_b32_e64 v22, 0, v22, s[48:49]
	v_or3_b32 v22, v173, v30, v22
	v_add_u32_e32 v22, v23, v22
	v_cmp_lt_u32_e64 s[52:53], v22, v15
	v_cndmask_b32_e64 v30, 0, v183, s[46:47]
	v_cndmask_b32_e64 v29, v29, 0, s[8:9]
	v_cndmask_b32_e64 v23, v31, v22, s[52:53]
	v_cndmask_b32_e32 v31, 0, v175, vcc
	v_or_b32_e32 v30, v31, v30
	v_cndmask_b32_e64 v21, 0, v21, s[48:49]
	v_or3_b32 v21, v30, v29, v21
	v_add_u32_e32 v21, v22, v21
	v_cmp_lt_u32_e64 s[56:57], v21, v15
	v_cndmask_b32_e32 v29, 0, v174, vcc
	v_cndmask_b32_e64 v28, v28, 0, s[8:9]
	v_cndmask_b32_e64 v22, v23, v21, s[56:57]
	v_cndmask_b32_e64 v23, 0, v182, s[46:47]
	v_or_b32_e32 v23, v29, v23
	v_cndmask_b32_e64 v20, 0, v20, s[48:49]
	v_or3_b32 v20, v23, v28, v20
	v_add_u32_e32 v20, v21, v20
	v_cmp_lt_u32_e64 s[58:59], v20, v15
	v_cndmask_b32_e32 v23, 0, v35, vcc
	v_cndmask_b32_e64 v19, 0, v19, s[48:49]
	v_cndmask_b32_e64 v21, v22, v20, s[58:59]
	v_cndmask_b32_e64 v22, 0, v181, s[46:47]
	v_or_b32_e32 v22, v23, v22
	v_cndmask_b32_e64 v23, v27, 0, s[8:9]
	v_or3_b32 v19, v22, v23, v19
	v_add_u32_e32 v19, v20, v19
	v_cmp_lt_u32_e64 s[60:61], v19, v15
	v_cndmask_b32_e32 v22, 0, v34, vcc
	v_cndmask_b32_e64 v18, 0, v18, s[48:49]
	v_cndmask_b32_e64 v20, v21, v19, s[60:61]
	v_cndmask_b32_e64 v21, 0, v180, s[46:47]
	v_or_b32_e32 v21, v22, v21
	v_cndmask_b32_e64 v22, v26, 0, s[8:9]
	v_or3_b32 v18, v21, v22, v18
	v_add_u32_e32 v18, v19, v18
	v_cmp_lt_u32_e64 s[62:63], v18, v15
	v_cndmask_b32_e32 v21, 0, v33, vcc
	v_cndmask_b32_e64 v17, 0, v17, s[48:49]
	v_cndmask_b32_e64 v19, v20, v18, s[62:63]
	v_cndmask_b32_e64 v20, 0, v179, s[46:47]
	v_or_b32_e32 v20, v21, v20
	v_cndmask_b32_e64 v21, v25, 0, s[8:9]
	v_or3_b32 v17, v20, v21, v17
	v_add_u32_e32 v17, v18, v17
	v_cmp_lt_u32_e64 s[64:65], v17, v15
	v_cndmask_b32_e32 v20, 0, v32, vcc
	v_cndmask_b32_e64 v16, 0, v16, s[48:49]
	v_cndmask_b32_e64 v18, v19, v17, s[64:65]
	v_cndmask_b32_e64 v19, 0, v178, s[46:47]
	v_or_b32_e32 v19, v20, v19
	v_cndmask_b32_e64 v20, v24, 0, s[8:9]
	v_or3_b32 v16, v19, v20, v16
	v_add_u32_e32 v16, v17, v16
	v_cndmask_b32_e64 v17, 8, 0, s[42:43]
	v_cndmask_b32_e64 v17, v17, 16, s[44:45]
	v_cndmask_b32_e64 v17, v17, 24, s[46:47]
	v_subb_co_u32_e64 v17, s[42:43], v17, v5, s[50:51]
	v_add_u32_e32 v17, 0x7e0, v17
	v_subbrev_co_u32_e64 v17, s[42:43], 0, v17, s[52:53]
	v_subbrev_co_u32_e64 v17, s[42:43], 0, v17, s[56:57]
	v_subbrev_co_u32_e64 v17, s[42:43], 0, v17, s[58:59]
	v_subbrev_co_u32_e64 v17, s[42:43], 0, v17, s[60:61]
	v_subbrev_co_u32_e64 v17, s[42:43], 0, v17, s[62:63]
	v_cmp_lt_u32_e32 vcc, v16, v15
	v_subbrev_co_u32_e64 v17, s[42:43], 0, v17, s[64:65]
	s_nop 0
	v_cndmask_b32_e32 v16, v18, v16, vcc
	v_subbrev_co_u32_e32 v17, vcc, 0, v17, vcc
	s_nop 0
	v_readlane_b32 s13, v17, s14
	v_readlane_b32 s12, v16, s14
	s_and_saveexec_b64 s[8:9], s[40:41]
	s_cbranch_execz .LBB0_1718
	s_lshr_b32 s12, s12, 16
	v_lshrrev_b32_e32 v15, 16, v15
	s_add_i32 s13, s13, 7
	s_lshr_b32 s14, s13, 3
	s_and_b32 s14, s14, 28
	s_xor_b32 s14, s14, s13
	s_lshl_b32 s14, s14, 2
	s_add_i32 s14, s14, 0
	s_add_i32 s11, s14, s11
	s_add_i32 s10, s10, 0x22000
	v_mov_b32_e32 v18, s10
	v_mov_b32_e32 v17, s11
	ds_read_b32 v16, v18
	ds_read_b32 v19, v17
	s_movk_i32 s10, 0x41
	v_subrev_u32_e32 v17, s12, v15
	s_waitcnt lgkmcnt(1)
	v_lshlrev_b32_e32 v15, 11, v16
	s_waitcnt lgkmcnt(0)
	v_lshrrev_b32_e32 v19, 16, v19
	v_cmp_gt_u32_e32 vcc, s10, v19
	v_or_b32_e32 v16, s13, v15
	ds_write_b64 v18, v[16:17]
	s_cbranch_vccnz .LBB0_1718
	v_mov_b32_e32 v15, s84
	ds_write_b32 v15, v186
	s_branch .LBB0_1718
